# P0 weight transposes (w_up/w_down, both layers): next item lines touched early into L2 (16 MiB stride) after the current item's 8 loads; counted waits bumped
# baseline (speedup 1.0000x reference)
.LBB0_504:
	s_andn2_b64 vcc, exec, s[6:7]
	s_cbranch_vccnz .LBB0_506
	s_cmpk_lt_u32 s8, 0x5240
	s_cselect_b32 s100, 0x1000000, 0
	s_cmpk_eq_i32 s50, 0x100
	s_cselect_b32 s100, s100, 0
	s_mov_b32 s101, 0
	s_and_b32 s6, s8, 0x7fc0
	s_ashr_i32 s43, s42, 31
	s_add_i32 s38, s6, 0xffffc5c0
	s_and_b32 s9, s8, 63
	s_lshl_b64 s[6:7], s[42:43], 26
	s_waitcnt lgkmcnt(0)
	s_add_u32 s10, s28, s6
	s_addc_u32 s11, s29, s7
	s_lshl_b64 s[6:7], s[38:39], 13
	s_add_u32 s6, s10, s6
	s_addc_u32 s7, s11, s7
	s_lshl_b32 s10, s9, 7
	s_add_u32 s10, s6, s10
	s_addc_u32 s11, s7, 0
	v_lshlrev_b32_e32 v0, 2, v6
	v_lshl_add_u64 v[114:115], s[10:11], 0, v[0:1]
	v_lshlrev_b32_e32 v0, 2, v10
	v_lshl_add_u64 v[2:3], v[114:115], 0, v[0:1]
	v_lshl_add_u64 v[170:171], v[2:3], 0, s[100:101]
	v_lshlrev_b32_e32 v0, 2, v28
	global_load_dwordx4 v[2:5], v[2:3], off
	v_lshl_add_u64 v[90:91], v[114:115], 0, v[0:1]
	v_lshl_add_u64 v[172:173], v[90:91], 0, s[100:101]
	global_load_dwordx4 v[90:93], v[90:91], off
	v_lshlrev_b32_e32 v0, 2, v30
	v_lshl_add_u64 v[94:95], v[114:115], 0, v[0:1]
	v_lshl_add_u64 v[174:175], v[94:95], 0, s[100:101]
	global_load_dwordx4 v[94:97], v[94:95], off
	v_lshlrev_b32_e32 v0, 2, v32
	v_lshl_add_u64 v[98:99], v[114:115], 0, v[0:1]
	v_lshl_add_u64 v[176:177], v[98:99], 0, s[100:101]
	global_load_dwordx4 v[98:101], v[98:99], off
	v_lshlrev_b32_e32 v0, 2, v34
	v_lshl_add_u64 v[102:103], v[114:115], 0, v[0:1]
	v_lshl_add_u64 v[178:179], v[102:103], 0, s[100:101]
	global_load_dwordx4 v[102:105], v[102:103], off
	v_lshlrev_b32_e32 v0, 2, v36
	v_lshl_add_u64 v[106:107], v[114:115], 0, v[0:1]
	v_lshl_add_u64 v[180:181], v[106:107], 0, s[100:101]
	global_load_dwordx4 v[106:109], v[106:107], off
	v_lshlrev_b32_e32 v0, 2, v38
	v_lshl_add_u64 v[110:111], v[114:115], 0, v[0:1]
	v_lshl_add_u64 v[182:183], v[110:111], 0, s[100:101]
	global_load_dwordx4 v[110:113], v[110:111], off
	v_lshlrev_b32_e32 v0, 2, v40
	v_lshl_add_u64 v[114:115], v[114:115], 0, v[0:1]
	v_lshl_add_u64 v[184:185], v[114:115], 0, s[100:101]
	global_load_dwordx4 v[114:117], v[114:115], off
	global_load_dword v186, v[170:171], off
	global_load_dword v186, v[172:173], off
	global_load_dword v186, v[174:175], off
	global_load_dword v186, v[176:177], off
	global_load_dword v186, v[178:179], off
	global_load_dword v186, v[180:181], off
	global_load_dword v186, v[182:183], off
	global_load_dword v186, v[184:185], off
	v_add_u32_e32 v0, v29, v7
	s_lshl_b64 s[6:7], s[42:43], 25
	s_add_u32 s6, s16, s6
	s_addc_u32 s7, s17, s7
	s_lshl_b32 s9, s9, 19
	s_add_u32 s9, s6, s9
	s_addc_u32 s43, s7, 0
	s_lshl_b64 s[6:7], s[38:39], 1
	s_add_u32 s6, s9, s6
	s_addc_u32 s7, s43, s7
	s_waitcnt vmcnt(15)
	ds_write2_b32 v0, v2, v3 offset1:1
	ds_write2_b32 v0, v4, v5 offset0:2 offset1:3
	v_add_u32_e32 v2, 0x420, v0
	s_waitcnt vmcnt(14)
	ds_write2_b32 v2, v90, v91 offset1:1
	v_add_u32_e32 v2, 0x428, v0
	ds_write2_b32 v2, v92, v93 offset1:1
	v_add_u32_e32 v2, 0x840, v0
	s_waitcnt vmcnt(13)
	ds_write2_b32 v2, v94, v95 offset1:1
	v_add_u32_e32 v2, 0x848, v0
	ds_write2_b32 v2, v96, v97 offset1:1
	v_add_u32_e32 v2, 0xc60, v0
	s_waitcnt vmcnt(12)
	ds_write2_b32 v2, v98, v99 offset1:1
	v_add_u32_e32 v2, 0xc68, v0
	ds_write2_b32 v2, v100, v101 offset1:1
	v_add_u32_e32 v2, 0x1080, v0
	s_waitcnt vmcnt(11)
	ds_write2_b32 v2, v102, v103 offset1:1
	v_add_u32_e32 v2, 0x1088, v0
	ds_write2_b32 v2, v104, v105 offset1:1
	v_add_u32_e32 v2, 0x14a0, v0
	s_waitcnt vmcnt(10)
	ds_write2_b32 v2, v106, v107 offset1:1
	v_add_u32_e32 v2, 0x14a8, v0
	ds_write2_b32 v2, v108, v109 offset1:1
	v_add_u32_e32 v2, 0x18c0, v0
	s_waitcnt vmcnt(9)
	ds_write2_b32 v2, v110, v111 offset1:1
	v_add_u32_e32 v2, 0x18c8, v0
	ds_write2_b32 v2, v112, v113 offset1:1
	v_add_u32_e32 v2, 0x1ce0, v0
	v_add_u32_e32 v0, 0x1ce8, v0
	s_waitcnt vmcnt(8)
	ds_write2_b32 v2, v114, v115 offset1:1
	ds_write2_b32 v0, v116, v117 offset1:1
	s_waitcnt lgkmcnt(0)
	ds_read2_b32 v[4:5], v31 offset0:33 offset1:41
	ds_read2_b32 v[94:95], v31 offset1:8
	ds_read2_b32 v[96:97], v31 offset0:66 offset1:74
	ds_read2_b32 v[98:99], v31 offset0:99 offset1:107
	ds_read2_b32 v[100:101], v31 offset0:132 offset1:140
	ds_read2_b32 v[102:103], v31 offset0:165 offset1:173
	ds_read2_b32 v[104:105], v31 offset0:198 offset1:206
	ds_read2_b32 v[106:107], v31 offset0:231 offset1:239
	v_lshlrev_b32_e32 v0, 1, v8
	v_lshl_add_u64 v[2:3], s[6:7], 0, v[0:1]
	v_lshlrev_b32_e32 v0, 1, v12
	s_waitcnt lgkmcnt(6)
	v_cvt_pk_bf16_f32 v90, v94, v4
	s_waitcnt lgkmcnt(4)
	v_cvt_pk_bf16_f32 v91, v96, v98
	s_waitcnt lgkmcnt(2)
	v_cvt_pk_bf16_f32 v92, v100, v102
	s_waitcnt lgkmcnt(0)
	v_cvt_pk_bf16_f32 v93, v104, v106
	v_lshl_add_u64 v[108:109], v[2:3], 0, v[0:1]
	v_lshlrev_b32_e32 v0, 1, v42
	global_store_dwordx4 v[108:109], v[90:93], off
	s_nop 1
	v_cvt_pk_bf16_f32 v90, v95, v5
	v_cvt_pk_bf16_f32 v91, v97, v99
	v_cvt_pk_bf16_f32 v92, v101, v103
	v_cvt_pk_bf16_f32 v93, v105, v107
	v_lshl_add_u64 v[4:5], v[2:3], 0, v[0:1]
	global_store_dwordx4 v[4:5], v[90:93], off
	ds_read2_b32 v[4:5], v31 offset0:49 offset1:57
	ds_read2_b32 v[94:95], v31 offset0:16 offset1:24
	ds_read2_b32 v[96:97], v31 offset0:82 offset1:90
	ds_read2_b32 v[98:99], v31 offset0:115 offset1:123
	ds_read2_b32 v[100:101], v31 offset0:148 offset1:156
	ds_read2_b32 v[102:103], v31 offset0:181 offset1:189
	ds_read2_b32 v[104:105], v31 offset0:214 offset1:222
	ds_read2_b32 v[106:107], v31 offset0:247 offset1:255
	v_lshlrev_b32_e32 v0, 1, v44
	s_waitcnt lgkmcnt(6)
	v_cvt_pk_bf16_f32 v90, v94, v4
	s_waitcnt lgkmcnt(4)
	v_cvt_pk_bf16_f32 v91, v96, v98
	s_waitcnt lgkmcnt(2)
	v_cvt_pk_bf16_f32 v92, v100, v102
	s_waitcnt lgkmcnt(0)
	v_cvt_pk_bf16_f32 v93, v104, v106
	v_lshl_add_u64 v[108:109], v[2:3], 0, v[0:1]
	v_lshlrev_b32_e32 v0, 1, v46
	global_store_dwordx4 v[108:109], v[90:93], off
	v_lshl_add_u64 v[2:3], v[2:3], 0, v[0:1]
	s_nop 0
	v_cvt_pk_bf16_f32 v90, v95, v5
	v_cvt_pk_bf16_f32 v91, v97, v99
	v_cvt_pk_bf16_f32 v92, v101, v103
	v_cvt_pk_bf16_f32 v93, v105, v107
	global_store_dwordx4 v[2:3], v[90:93], off
	s_waitcnt lgkmcnt(0)

.LBB0_507:
	s_andn2_b64 vcc, exec, s[6:7]
	s_cbranch_vccnz .LBB0_509
	s_cmpk_lt_u32 s8, 0x3240
	s_cselect_b32 s100, 0x1000000, 0
	s_cmpk_eq_i32 s50, 0x100
	s_cselect_b32 s100, s100, 0
	s_mov_b32 s101, 0
	s_add_i32 s9, s8, 0xffffe5c0
	s_ashr_i32 s43, s42, 31
	s_and_b32 s55, s9, 0xff
	s_lshl_b64 s[6:7], s[42:43], 26
	s_waitcnt lgkmcnt(0)
	s_add_u32 s10, s46, s6
	s_addc_u32 s11, s47, s7
	s_lshr_b32 s6, s9, 2
	s_and_b32 s38, s6, 0x3fffffc0
	s_lshl_b64 s[6:7], s[38:39], 15
	s_add_u32 s6, s10, s6
	s_addc_u32 s7, s11, s7
	s_lshl_b32 s9, s55, 7
	s_add_u32 s10, s6, s9
	s_addc_u32 s11, s7, 0
	v_lshlrev_b32_e32 v0, 2, v6
	v_lshl_add_u64 v[114:115], s[10:11], 0, v[0:1]
	v_lshlrev_b32_e32 v0, 2, v12
	v_lshl_add_u64 v[2:3], v[114:115], 0, v[0:1]
	v_lshl_add_u64 v[170:171], v[2:3], 0, s[100:101]
	v_lshlrev_b32_e32 v0, 2, v42
	global_load_dwordx4 v[2:5], v[2:3], off
	v_lshl_add_u64 v[90:91], v[114:115], 0, v[0:1]
	v_lshl_add_u64 v[172:173], v[90:91], 0, s[100:101]
	global_load_dwordx4 v[90:93], v[90:91], off
	v_lshlrev_b32_e32 v0, 2, v44
	v_lshl_add_u64 v[94:95], v[114:115], 0, v[0:1]
	v_lshl_add_u64 v[174:175], v[94:95], 0, s[100:101]
	global_load_dwordx4 v[94:97], v[94:95], off
	v_lshlrev_b32_e32 v0, 2, v46
	v_lshl_add_u64 v[98:99], v[114:115], 0, v[0:1]
	v_lshl_add_u64 v[176:177], v[98:99], 0, s[100:101]
	global_load_dwordx4 v[98:101], v[98:99], off
	v_mov_b32_e32 v73, v1
	v_lshl_add_u64 v[102:103], v[114:115], 0, v[72:73]
	v_lshl_add_u64 v[178:179], v[102:103], 0, s[100:101]
	global_load_dwordx4 v[102:105], v[102:103], off
	v_mov_b32_e32 v75, v1
	v_lshl_add_u64 v[106:107], v[114:115], 0, v[74:75]
	v_lshl_add_u64 v[180:181], v[106:107], 0, s[100:101]
	global_load_dwordx4 v[106:109], v[106:107], off
	v_mov_b32_e32 v77, v1
	v_lshl_add_u64 v[110:111], v[114:115], 0, v[76:77]
	v_lshl_add_u64 v[182:183], v[110:111], 0, s[100:101]
	global_load_dwordx4 v[110:113], v[110:111], off
	v_mov_b32_e32 v79, v1
	v_lshl_add_u64 v[114:115], v[114:115], 0, v[78:79]
	v_lshl_add_u64 v[184:185], v[114:115], 0, s[100:101]
	global_load_dwordx4 v[114:117], v[114:115], off
	global_load_dword v186, v[170:171], off
	global_load_dword v186, v[172:173], off
	global_load_dword v186, v[174:175], off
	global_load_dword v186, v[176:177], off
	global_load_dword v186, v[178:179], off
	global_load_dword v186, v[180:181], off
	global_load_dword v186, v[182:183], off
	global_load_dword v186, v[184:185], off
	v_add_u32_e32 v0, v29, v7
	s_lshl_b64 s[6:7], s[42:43], 25
	s_add_u32 s6, s14, s6
	s_addc_u32 s7, s15, s7
	s_lshl_b32 s9, s55, 17
	s_add_u32 s6, s6, s9
	s_addc_u32 s7, s7, 0
	s_lshl_b32 s9, s38, 1
	s_add_u32 s6, s6, s9
	s_addc_u32 s7, s7, 0
	s_waitcnt vmcnt(15)
	ds_write2_b32 v0, v2, v3 offset1:1
	ds_write2_b32 v0, v4, v5 offset0:2 offset1:3
	v_add_u32_e32 v2, 0x420, v0
	s_waitcnt vmcnt(14)
	ds_write2_b32 v2, v90, v91 offset1:1
	v_add_u32_e32 v2, 0x428, v0
	ds_write2_b32 v2, v92, v93 offset1:1
	v_add_u32_e32 v2, 0x840, v0
	s_waitcnt vmcnt(13)
	ds_write2_b32 v2, v94, v95 offset1:1
	v_add_u32_e32 v2, 0x848, v0
	ds_write2_b32 v2, v96, v97 offset1:1
	v_add_u32_e32 v2, 0xc60, v0
	s_waitcnt vmcnt(12)
	ds_write2_b32 v2, v98, v99 offset1:1
	v_add_u32_e32 v2, 0xc68, v0
	ds_write2_b32 v2, v100, v101 offset1:1
	v_add_u32_e32 v2, 0x1080, v0
	s_waitcnt vmcnt(11)
	ds_write2_b32 v2, v102, v103 offset1:1
	v_add_u32_e32 v2, 0x1088, v0
	ds_write2_b32 v2, v104, v105 offset1:1
	v_add_u32_e32 v2, 0x14a0, v0
	s_waitcnt vmcnt(10)
	ds_write2_b32 v2, v106, v107 offset1:1
	v_add_u32_e32 v2, 0x14a8, v0
	ds_write2_b32 v2, v108, v109 offset1:1
	v_add_u32_e32 v2, 0x18c0, v0
	s_waitcnt vmcnt(9)
	ds_write2_b32 v2, v110, v111 offset1:1
	v_add_u32_e32 v2, 0x18c8, v0
	ds_write2_b32 v2, v112, v113 offset1:1
	v_add_u32_e32 v2, 0x1ce0, v0
	v_add_u32_e32 v0, 0x1ce8, v0
	s_waitcnt vmcnt(8)
	ds_write2_b32 v2, v114, v115 offset1:1
	ds_write2_b32 v0, v116, v117 offset1:1
	s_waitcnt lgkmcnt(0)
	ds_read2_b32 v[4:5], v31 offset0:33 offset1:41
	ds_read2_b32 v[94:95], v31 offset1:8
	ds_read2_b32 v[96:97], v31 offset0:66 offset1:74
	ds_read2_b32 v[98:99], v31 offset0:99 offset1:107
	ds_read2_b32 v[100:101], v31 offset0:132 offset1:140
	ds_read2_b32 v[102:103], v31 offset0:165 offset1:173
	ds_read2_b32 v[104:105], v31 offset0:198 offset1:206
	ds_read2_b32 v[106:107], v31 offset0:231 offset1:239
	v_lshlrev_b32_e32 v0, 1, v8
	v_lshl_add_u64 v[2:3], s[6:7], 0, v[0:1]
	v_lshlrev_b32_e32 v0, 1, v10
	s_waitcnt lgkmcnt(6)
	v_cvt_pk_bf16_f32 v90, v94, v4
	s_waitcnt lgkmcnt(4)
	v_cvt_pk_bf16_f32 v91, v96, v98
	s_waitcnt lgkmcnt(2)
	v_cvt_pk_bf16_f32 v92, v100, v102
	s_waitcnt lgkmcnt(0)
	v_cvt_pk_bf16_f32 v93, v104, v106
	v_lshl_add_u64 v[108:109], v[2:3], 0, v[0:1]
	v_lshlrev_b32_e32 v0, 1, v28
	global_store_dwordx4 v[108:109], v[90:93], off
	s_nop 1
	v_cvt_pk_bf16_f32 v90, v95, v5
	v_cvt_pk_bf16_f32 v91, v97, v99
	v_cvt_pk_bf16_f32 v92, v101, v103
	v_cvt_pk_bf16_f32 v93, v105, v107
	v_lshl_add_u64 v[4:5], v[2:3], 0, v[0:1]
	global_store_dwordx4 v[4:5], v[90:93], off
	ds_read2_b32 v[4:5], v31 offset0:49 offset1:57
	ds_read2_b32 v[94:95], v31 offset0:16 offset1:24
	ds_read2_b32 v[96:97], v31 offset0:82 offset1:90
	ds_read2_b32 v[98:99], v31 offset0:115 offset1:123
	ds_read2_b32 v[100:101], v31 offset0:148 offset1:156
	ds_read2_b32 v[102:103], v31 offset0:181 offset1:189
	ds_read2_b32 v[104:105], v31 offset0:214 offset1:222
	ds_read2_b32 v[106:107], v31 offset0:247 offset1:255
	v_lshlrev_b32_e32 v0, 1, v30
	s_waitcnt lgkmcnt(6)
	v_cvt_pk_bf16_f32 v90, v94, v4
	s_waitcnt lgkmcnt(4)
	v_cvt_pk_bf16_f32 v91, v96, v98
	s_waitcnt lgkmcnt(2)
	v_cvt_pk_bf16_f32 v92, v100, v102
	s_waitcnt lgkmcnt(0)
	v_cvt_pk_bf16_f32 v93, v104, v106
	v_lshl_add_u64 v[108:109], v[2:3], 0, v[0:1]
	v_lshlrev_b32_e32 v0, 1, v32
	global_store_dwordx4 v[108:109], v[90:93], off
	v_lshl_add_u64 v[2:3], v[2:3], 0, v[0:1]
	s_nop 0
	v_cvt_pk_bf16_f32 v90, v95, v5
	v_cvt_pk_bf16_f32 v91, v97, v99
	v_cvt_pk_bf16_f32 v92, v101, v103
	v_cvt_pk_bf16_f32 v93, v105, v107
	global_store_dwordx4 v[2:3], v[90:93], off
	s_waitcnt lgkmcnt(0)

.LBB0_540:
	s_andn2_b64 vcc, exec, s[6:7]
	s_cbranch_vccnz .LBB0_542
	s_cmpk_lt_u32 s8, 0x5240
	s_cselect_b32 s100, 0x1000000, 0
	s_cmpk_eq_i32 s50, 0x100
	s_cselect_b32 s100, s100, 0
	s_mov_b32 s101, 0
	s_and_b32 s6, s8, 0x7fc0
	s_ashr_i32 s43, s42, 31
	s_add_i32 s38, s6, 0xffffc5c0
	s_and_b32 s54, s9, 63
	s_lshl_b64 s[6:7], s[42:43], 26
	s_waitcnt lgkmcnt(0)
	s_add_u32 s10, s28, s6
	s_addc_u32 s11, s29, s7
	s_lshl_b64 s[6:7], s[38:39], 13
	s_add_u32 s6, s10, s6
	s_addc_u32 s7, s11, s7
	s_lshl_b32 s10, s54, 7
	s_add_u32 s10, s6, s10
	s_addc_u32 s11, s7, 0
	v_lshlrev_b32_e32 v0, 2, v6
	v_lshl_add_u64 v[100:101], s[10:11], 0, v[0:1]
	v_lshlrev_b32_e32 v0, 2, v10
	v_lshl_add_u64 v[2:3], v[100:101], 0, v[0:1]
	v_lshl_add_u64 v[170:171], v[2:3], 0, s[100:101]
	v_lshlrev_b32_e32 v0, 2, v28
	global_load_dwordx4 v[2:5], v[2:3], off
	v_lshl_add_u64 v[76:77], v[100:101], 0, v[0:1]
	v_lshl_add_u64 v[172:173], v[76:77], 0, s[100:101]
	global_load_dwordx4 v[76:79], v[76:77], off
	v_lshlrev_b32_e32 v0, 2, v30
	v_lshl_add_u64 v[80:81], v[100:101], 0, v[0:1]
	v_lshl_add_u64 v[174:175], v[80:81], 0, s[100:101]
	global_load_dwordx4 v[80:83], v[80:81], off
	v_lshlrev_b32_e32 v0, 2, v32
	v_lshl_add_u64 v[84:85], v[100:101], 0, v[0:1]
	v_lshl_add_u64 v[176:177], v[84:85], 0, s[100:101]
	global_load_dwordx4 v[84:87], v[84:85], off
	v_lshlrev_b32_e32 v0, 2, v34
	v_lshl_add_u64 v[88:89], v[100:101], 0, v[0:1]
	v_lshl_add_u64 v[178:179], v[88:89], 0, s[100:101]
	global_load_dwordx4 v[88:91], v[88:89], off
	v_lshlrev_b32_e32 v0, 2, v36
	v_lshl_add_u64 v[92:93], v[100:101], 0, v[0:1]
	v_lshl_add_u64 v[180:181], v[92:93], 0, s[100:101]
	global_load_dwordx4 v[92:95], v[92:93], off
	v_lshlrev_b32_e32 v0, 2, v38
	v_lshl_add_u64 v[96:97], v[100:101], 0, v[0:1]
	v_lshl_add_u64 v[182:183], v[96:97], 0, s[100:101]
	global_load_dwordx4 v[96:99], v[96:97], off
	v_lshlrev_b32_e32 v0, 2, v40
	v_lshl_add_u64 v[100:101], v[100:101], 0, v[0:1]
	v_lshl_add_u64 v[184:185], v[100:101], 0, s[100:101]
	global_load_dwordx4 v[100:103], v[100:101], off
	global_load_dword v186, v[170:171], off
	global_load_dword v186, v[172:173], off
	global_load_dword v186, v[174:175], off
	global_load_dword v186, v[176:177], off
	global_load_dword v186, v[178:179], off
	global_load_dword v186, v[180:181], off
	global_load_dword v186, v[182:183], off
	global_load_dword v186, v[184:185], off
	v_add_u32_e32 v0, v29, v7
	s_lshl_b64 s[6:7], s[42:43], 25
	s_add_u32 s6, s16, s6
	s_addc_u32 s7, s17, s7
	s_lshl_b32 s43, s54, 19
	s_add_u32 s43, s6, s43
	s_addc_u32 s54, s7, 0
	s_lshl_b64 s[6:7], s[38:39], 1
	s_add_u32 s6, s43, s6
	s_addc_u32 s7, s54, s7
	s_waitcnt vmcnt(15)
	ds_write2_b32 v0, v2, v3 offset1:1
	ds_write2_b32 v0, v4, v5 offset0:2 offset1:3
	v_add_u32_e32 v2, 0x420, v0
	s_waitcnt vmcnt(14)
	ds_write2_b32 v2, v76, v77 offset1:1
	v_add_u32_e32 v2, 0x428, v0
	ds_write2_b32 v2, v78, v79 offset1:1
	v_add_u32_e32 v2, 0x840, v0
	s_waitcnt vmcnt(13)
	ds_write2_b32 v2, v80, v81 offset1:1
	v_add_u32_e32 v2, 0x848, v0
	ds_write2_b32 v2, v82, v83 offset1:1
	v_add_u32_e32 v2, 0xc60, v0
	s_waitcnt vmcnt(12)
	ds_write2_b32 v2, v84, v85 offset1:1
	v_add_u32_e32 v2, 0xc68, v0
	ds_write2_b32 v2, v86, v87 offset1:1
	v_add_u32_e32 v2, 0x1080, v0
	s_waitcnt vmcnt(11)
	ds_write2_b32 v2, v88, v89 offset1:1
	v_add_u32_e32 v2, 0x1088, v0
	ds_write2_b32 v2, v90, v91 offset1:1
	v_add_u32_e32 v2, 0x14a0, v0
	s_waitcnt vmcnt(10)
	ds_write2_b32 v2, v92, v93 offset1:1
	v_add_u32_e32 v2, 0x14a8, v0
	ds_write2_b32 v2, v94, v95 offset1:1
	v_add_u32_e32 v2, 0x18c0, v0
	s_waitcnt vmcnt(9)
	ds_write2_b32 v2, v96, v97 offset1:1
	v_add_u32_e32 v2, 0x18c8, v0
	ds_write2_b32 v2, v98, v99 offset1:1
	v_add_u32_e32 v2, 0x1ce0, v0
	v_add_u32_e32 v0, 0x1ce8, v0
	s_waitcnt vmcnt(8)
	ds_write2_b32 v2, v100, v101 offset1:1
	ds_write2_b32 v0, v102, v103 offset1:1
	s_waitcnt lgkmcnt(0)
	ds_read2_b32 v[4:5], v31 offset0:33 offset1:41
	ds_read2_b32 v[80:81], v31 offset1:8
	ds_read2_b32 v[82:83], v31 offset0:66 offset1:74
	ds_read2_b32 v[84:85], v31 offset0:99 offset1:107
	ds_read2_b32 v[86:87], v31 offset0:132 offset1:140
	ds_read2_b32 v[88:89], v31 offset0:165 offset1:173
	ds_read2_b32 v[90:91], v31 offset0:198 offset1:206
	ds_read2_b32 v[92:93], v31 offset0:231 offset1:239
	v_lshlrev_b32_e32 v0, 1, v8
	v_lshl_add_u64 v[2:3], s[6:7], 0, v[0:1]
	v_lshlrev_b32_e32 v0, 1, v12
	s_waitcnt lgkmcnt(6)
	v_cvt_pk_bf16_f32 v76, v80, v4
	s_waitcnt lgkmcnt(4)
	v_cvt_pk_bf16_f32 v77, v82, v84
	s_waitcnt lgkmcnt(2)
	v_cvt_pk_bf16_f32 v78, v86, v88
	s_waitcnt lgkmcnt(0)
	v_cvt_pk_bf16_f32 v79, v90, v92
	v_lshl_add_u64 v[94:95], v[2:3], 0, v[0:1]
	v_lshlrev_b32_e32 v0, 1, v42
	global_store_dwordx4 v[94:95], v[76:79], off
	s_nop 1
	v_cvt_pk_bf16_f32 v76, v81, v5
	v_cvt_pk_bf16_f32 v77, v83, v85
	v_cvt_pk_bf16_f32 v78, v87, v89
	v_cvt_pk_bf16_f32 v79, v91, v93
	v_lshl_add_u64 v[4:5], v[2:3], 0, v[0:1]
	global_store_dwordx4 v[4:5], v[76:79], off
	ds_read2_b32 v[4:5], v31 offset0:49 offset1:57
	ds_read2_b32 v[80:81], v31 offset0:16 offset1:24
	ds_read2_b32 v[82:83], v31 offset0:82 offset1:90
	ds_read2_b32 v[84:85], v31 offset0:115 offset1:123
	ds_read2_b32 v[86:87], v31 offset0:148 offset1:156
	ds_read2_b32 v[88:89], v31 offset0:181 offset1:189
	ds_read2_b32 v[90:91], v31 offset0:214 offset1:222
	ds_read2_b32 v[92:93], v31 offset0:247 offset1:255
	v_lshlrev_b32_e32 v0, 1, v44
	s_waitcnt lgkmcnt(6)
	v_cvt_pk_bf16_f32 v76, v80, v4
	s_waitcnt lgkmcnt(4)
	v_cvt_pk_bf16_f32 v77, v82, v84
	s_waitcnt lgkmcnt(2)
	v_cvt_pk_bf16_f32 v78, v86, v88
	s_waitcnt lgkmcnt(0)
	v_cvt_pk_bf16_f32 v79, v90, v92
	v_lshl_add_u64 v[94:95], v[2:3], 0, v[0:1]
	v_lshlrev_b32_e32 v0, 1, v46
	global_store_dwordx4 v[94:95], v[76:79], off
	v_lshl_add_u64 v[2:3], v[2:3], 0, v[0:1]
	s_nop 0
	v_cvt_pk_bf16_f32 v76, v81, v5
	v_cvt_pk_bf16_f32 v77, v83, v85
	v_cvt_pk_bf16_f32 v78, v87, v89
	v_cvt_pk_bf16_f32 v79, v91, v93
	global_store_dwordx4 v[2:3], v[76:79], off
	s_waitcnt lgkmcnt(0)

.LBB0_543:
	s_andn2_b64 vcc, exec, s[6:7]
	s_cbranch_vccnz .LBB0_545
	s_cmpk_lt_u32 s8, 0x3240
	s_cselect_b32 s100, 0x1000000, 0
	s_cmpk_eq_i32 s50, 0x100
	s_cselect_b32 s100, s100, 0
	s_mov_b32 s101, 0
	s_ashr_i32 s43, s42, 31
	s_and_b32 s54, s9, 0xff
	s_lshl_b64 s[6:7], s[42:43], 26
	s_waitcnt lgkmcnt(0)
	s_add_u32 s10, s46, s6
	s_addc_u32 s11, s47, s7
	s_lshr_b32 s6, s9, 2
	s_and_b32 s38, s6, 0x3fffffc0
	s_lshl_b64 s[6:7], s[38:39], 15
	s_add_u32 s6, s10, s6
	s_addc_u32 s7, s11, s7
	s_lshl_b32 s10, s54, 7
	s_add_u32 s10, s6, s10
	s_addc_u32 s11, s7, 0
	v_lshlrev_b32_e32 v0, 2, v6
	v_lshl_add_u64 v[100:101], s[10:11], 0, v[0:1]
	v_lshlrev_b32_e32 v0, 2, v12
	v_lshl_add_u64 v[2:3], v[100:101], 0, v[0:1]
	v_lshl_add_u64 v[170:171], v[2:3], 0, s[100:101]
	v_lshlrev_b32_e32 v0, 2, v42
	global_load_dwordx4 v[2:5], v[2:3], off
	v_lshl_add_u64 v[76:77], v[100:101], 0, v[0:1]
	v_lshl_add_u64 v[172:173], v[76:77], 0, s[100:101]
	global_load_dwordx4 v[76:79], v[76:77], off
	v_lshlrev_b32_e32 v0, 2, v44
	v_lshl_add_u64 v[80:81], v[100:101], 0, v[0:1]
	v_lshl_add_u64 v[174:175], v[80:81], 0, s[100:101]
	global_load_dwordx4 v[80:83], v[80:81], off
	v_lshlrev_b32_e32 v0, 2, v46
	v_lshl_add_u64 v[84:85], v[100:101], 0, v[0:1]
	v_lshl_add_u64 v[176:177], v[84:85], 0, s[100:101]
	global_load_dwordx4 v[84:87], v[84:85], off
	v_mov_b32_e32 v69, v1
	v_lshl_add_u64 v[88:89], v[100:101], 0, v[68:69]
	v_lshl_add_u64 v[178:179], v[88:89], 0, s[100:101]
	global_load_dwordx4 v[88:91], v[88:89], off
	v_mov_b32_e32 v71, v1
	v_lshl_add_u64 v[92:93], v[100:101], 0, v[70:71]
	v_lshl_add_u64 v[180:181], v[92:93], 0, s[100:101]
	global_load_dwordx4 v[92:95], v[92:93], off
	v_mov_b32_e32 v73, v1
	v_lshl_add_u64 v[96:97], v[100:101], 0, v[72:73]
	v_lshl_add_u64 v[182:183], v[96:97], 0, s[100:101]
	global_load_dwordx4 v[96:99], v[96:97], off
	v_mov_b32_e32 v75, v1
	v_lshl_add_u64 v[100:101], v[100:101], 0, v[74:75]
	v_lshl_add_u64 v[184:185], v[100:101], 0, s[100:101]
	global_load_dwordx4 v[100:103], v[100:101], off
	global_load_dword v186, v[170:171], off
	global_load_dword v186, v[172:173], off
	global_load_dword v186, v[174:175], off
	global_load_dword v186, v[176:177], off
	global_load_dword v186, v[178:179], off
	global_load_dword v186, v[180:181], off
	global_load_dword v186, v[182:183], off
	global_load_dword v186, v[184:185], off
	v_add_u32_e32 v0, v29, v7
	s_lshl_b64 s[6:7], s[42:43], 25
	s_add_u32 s6, s14, s6
	s_addc_u32 s7, s15, s7
	s_lshl_b32 s43, s54, 17
	s_add_u32 s6, s6, s43
	s_addc_u32 s7, s7, 0
	s_lshl_b32 s38, s38, 1
	s_add_u32 s6, s6, s38
	s_addc_u32 s7, s7, 0
	s_waitcnt vmcnt(15)
	ds_write2_b32 v0, v2, v3 offset1:1
	ds_write2_b32 v0, v4, v5 offset0:2 offset1:3
	v_add_u32_e32 v2, 0x420, v0
	s_waitcnt vmcnt(14)
	ds_write2_b32 v2, v76, v77 offset1:1
	v_add_u32_e32 v2, 0x428, v0
	ds_write2_b32 v2, v78, v79 offset1:1
	v_add_u32_e32 v2, 0x840, v0
	s_waitcnt vmcnt(13)
	ds_write2_b32 v2, v80, v81 offset1:1
	v_add_u32_e32 v2, 0x848, v0
	ds_write2_b32 v2, v82, v83 offset1:1
	v_add_u32_e32 v2, 0xc60, v0
	s_waitcnt vmcnt(12)
	ds_write2_b32 v2, v84, v85 offset1:1
	v_add_u32_e32 v2, 0xc68, v0
	ds_write2_b32 v2, v86, v87 offset1:1
	v_add_u32_e32 v2, 0x1080, v0
	s_waitcnt vmcnt(11)
	ds_write2_b32 v2, v88, v89 offset1:1
	v_add_u32_e32 v2, 0x1088, v0
	ds_write2_b32 v2, v90, v91 offset1:1
	v_add_u32_e32 v2, 0x14a0, v0
	s_waitcnt vmcnt(10)
	ds_write2_b32 v2, v92, v93 offset1:1
	v_add_u32_e32 v2, 0x14a8, v0
	ds_write2_b32 v2, v94, v95 offset1:1
	v_add_u32_e32 v2, 0x18c0, v0
	s_waitcnt vmcnt(9)
	ds_write2_b32 v2, v96, v97 offset1:1
	v_add_u32_e32 v2, 0x18c8, v0
	ds_write2_b32 v2, v98, v99 offset1:1
	v_add_u32_e32 v2, 0x1ce0, v0
	v_add_u32_e32 v0, 0x1ce8, v0
	s_waitcnt vmcnt(8)
	ds_write2_b32 v2, v100, v101 offset1:1
	ds_write2_b32 v0, v102, v103 offset1:1
	s_waitcnt lgkmcnt(0)
	ds_read2_b32 v[4:5], v31 offset0:33 offset1:41
	ds_read2_b32 v[80:81], v31 offset1:8
	ds_read2_b32 v[82:83], v31 offset0:66 offset1:74
	ds_read2_b32 v[84:85], v31 offset0:99 offset1:107
	ds_read2_b32 v[86:87], v31 offset0:132 offset1:140
	ds_read2_b32 v[88:89], v31 offset0:165 offset1:173
	ds_read2_b32 v[90:91], v31 offset0:198 offset1:206
	ds_read2_b32 v[92:93], v31 offset0:231 offset1:239
	v_lshlrev_b32_e32 v0, 1, v8
	v_lshl_add_u64 v[2:3], s[6:7], 0, v[0:1]
	v_lshlrev_b32_e32 v0, 1, v10
	s_waitcnt lgkmcnt(6)
	v_cvt_pk_bf16_f32 v76, v80, v4
	s_waitcnt lgkmcnt(4)
	v_cvt_pk_bf16_f32 v77, v82, v84
	s_waitcnt lgkmcnt(2)
	v_cvt_pk_bf16_f32 v78, v86, v88
	s_waitcnt lgkmcnt(0)
	v_cvt_pk_bf16_f32 v79, v90, v92
	v_lshl_add_u64 v[94:95], v[2:3], 0, v[0:1]
	v_lshlrev_b32_e32 v0, 1, v28
	global_store_dwordx4 v[94:95], v[76:79], off
	s_nop 1
	v_cvt_pk_bf16_f32 v76, v81, v5
	v_cvt_pk_bf16_f32 v77, v83, v85
	v_cvt_pk_bf16_f32 v78, v87, v89
	v_cvt_pk_bf16_f32 v79, v91, v93
	v_lshl_add_u64 v[4:5], v[2:3], 0, v[0:1]
	global_store_dwordx4 v[4:5], v[76:79], off
	ds_read2_b32 v[4:5], v31 offset0:49 offset1:57
	ds_read2_b32 v[80:81], v31 offset0:16 offset1:24
	ds_read2_b32 v[82:83], v31 offset0:82 offset1:90
	ds_read2_b32 v[84:85], v31 offset0:115 offset1:123
	ds_read2_b32 v[86:87], v31 offset0:148 offset1:156
	ds_read2_b32 v[88:89], v31 offset0:181 offset1:189
	ds_read2_b32 v[90:91], v31 offset0:214 offset1:222
	ds_read2_b32 v[92:93], v31 offset0:247 offset1:255
	v_lshlrev_b32_e32 v0, 1, v30
	s_waitcnt lgkmcnt(6)
	v_cvt_pk_bf16_f32 v76, v80, v4
	s_waitcnt lgkmcnt(4)
	v_cvt_pk_bf16_f32 v77, v82, v84
	s_waitcnt lgkmcnt(2)
	v_cvt_pk_bf16_f32 v78, v86, v88
	s_waitcnt lgkmcnt(0)
	v_cvt_pk_bf16_f32 v79, v90, v92
	v_lshl_add_u64 v[94:95], v[2:3], 0, v[0:1]
	v_lshlrev_b32_e32 v0, 1, v32
	global_store_dwordx4 v[94:95], v[76:79], off
	v_lshl_add_u64 v[2:3], v[2:3], 0, v[0:1]
	s_nop 0
	v_cvt_pk_bf16_f32 v76, v81, v5
	v_cvt_pk_bf16_f32 v77, v83, v85
	v_cvt_pk_bf16_f32 v78, v87, v89
	v_cvt_pk_bf16_f32 v79, v91, v93
	global_store_dwordx4 v[2:3], v[76:79], off
	s_waitcnt lgkmcnt(0)

	.amdhsa_kernel _Z8mega_fwd4Args
		.amdhsa_group_segment_fixed_size 0
		.amdhsa_private_segment_fixed_size 0
		.amdhsa_kernarg_size 512
		.amdhsa_user_sgpr_count 2
		.amdhsa_user_sgpr_dispatch_ptr 0
		.amdhsa_user_sgpr_queue_ptr 0
		.amdhsa_user_sgpr_kernarg_segment_ptr 1
		.amdhsa_user_sgpr_dispatch_id 0
		.amdhsa_user_sgpr_kernarg_preload_length 0
		.amdhsa_user_sgpr_kernarg_preload_offset 0
		.amdhsa_user_sgpr_private_segment_size 0
		.amdhsa_uses_dynamic_stack 0
		.amdhsa_enable_private_segment 0
		.amdhsa_system_sgpr_workgroup_id_x 1
		.amdhsa_system_sgpr_workgroup_id_y 0
		.amdhsa_system_sgpr_workgroup_id_z 0
		.amdhsa_system_sgpr_workgroup_info 0
		.amdhsa_system_vgpr_workitem_id 2
		.amdhsa_next_free_vgpr 255
		.amdhsa_next_free_sgpr 102
		.amdhsa_accum_offset 256
		.amdhsa_reserve_vcc 1
		.amdhsa_float_round_mode_32 0
		.amdhsa_float_round_mode_16_64 0
		.amdhsa_float_denorm_mode_32 3
		.amdhsa_float_denorm_mode_16_64 3
		.amdhsa_dx10_clamp 1
		.amdhsa_ieee_mode 1
		.amdhsa_fp16_overflow 0
		.amdhsa_tg_split 0
		.amdhsa_exception_fp_ieee_invalid_op 0
		.amdhsa_exception_fp_denorm_src 0
		.amdhsa_exception_fp_ieee_div_zero 0
		.amdhsa_exception_fp_ieee_overflow 0
		.amdhsa_exception_fp_ieee_underflow 0
		.amdhsa_exception_fp_ieee_inexact 0
		.amdhsa_exception_int_div_zero 0
	.end_amdhsa_kernel

.Lfunc_end0:
	.size	_Z8mega_fwd4Args, .Lfunc_end0-_Z8mega_fwd4Args
	.set _Z8mega_fwd4Args.num_vgpr, 255
	.set _Z8mega_fwd4Args.num_agpr, 0
	.set _Z8mega_fwd4Args.numbered_sgpr, 102
	.set _Z8mega_fwd4Args.num_named_barrier, 0
	.set _Z8mega_fwd4Args.private_seg_size, 0
	.set _Z8mega_fwd4Args.uses_vcc, 1
	.set _Z8mega_fwd4Args.uses_flat_scratch, 0
	.set _Z8mega_fwd4Args.has_dyn_sized_stack, 0
	.set _Z8mega_fwd4Args.has_recursion, 0
	.set _Z8mega_fwd4Args.has_indirect_call, 0

amdhsa.kernels:
  - .agpr_count:     0
    .args:
      - .offset:         0
        .size:           256
        .value_kind:     by_value
      - .offset:         256
        .size:           4
        .value_kind:     hidden_block_count_x
      - .offset:         260
        .size:           4
        .value_kind:     hidden_block_count_y
      - .offset:         264
        .size:           4
        .value_kind:     hidden_block_count_z
      - .offset:         268
        .size:           2
        .value_kind:     hidden_group_size_x
      - .offset:         270
        .size:           2
        .value_kind:     hidden_group_size_y
      - .offset:         272
        .size:           2
        .value_kind:     hidden_group_size_z
      - .offset:         274
        .size:           2
        .value_kind:     hidden_remainder_x
      - .offset:         276
        .size:           2
        .value_kind:     hidden_remainder_y
      - .offset:         278
        .size:           2
        .value_kind:     hidden_remainder_z
      - .offset:         296
        .size:           8
        .value_kind:     hidden_global_offset_x
      - .offset:         304
        .size:           8
        .value_kind:     hidden_global_offset_y
      - .offset:         312
        .size:           8
        .value_kind:     hidden_global_offset_z
      - .offset:         320
        .size:           2
        .value_kind:     hidden_grid_dims
      - .offset:         344
        .size:           8
        .value_kind:     hidden_multigrid_sync_arg
      - .offset:         376
        .size:           4
        .value_kind:     hidden_dynamic_lds_size
    .group_segment_fixed_size: 0
    .kernarg_segment_align: 8
    .kernarg_segment_size: 512
    .language:       OpenCL C
    .language_version:
      - 2
      - 0
    .max_flat_workgroup_size: 512
    .name:           _Z8mega_fwd4Args
    .private_segment_fixed_size: 0
    .sgpr_count:     108
    .sgpr_spill_count: 149
    .symbol:         _Z8mega_fwd4Args.kd
    .uniform_work_group_size: 1
    .uses_dynamic_stack: false
    .vgpr_count:     255
    .vgpr_spill_count: 0
    .wavefront_size: 64
